# P1 skinny GEMM (sample rows): all A/B fragment loads of a K trip issued up front with counted vmcnt instead of load-wait-mfma chains; plus earlier attn/state-copy edits
# speedup vs baseline: 1.0215x; 1.0004x over previous
; #define MFMA16(a, b, c) __builtin_amdgcn_mfma_f32_16x16x32_bf16((a), (b), (c), 0, 0, 0)
;     ...
;             if (glu) {
; #pragma unroll 8
;                 for (int k0 = 0; k0 < Kh; k0 += 32) { const bf16x8 a = *(const bf16x8*)(ap + k0);
;                     acc[0] = MFMA16(*(const bf16x8*)(bp + k0), a, acc[0]); acc[1] = MFMA16(*(const bf16x8*)(bp + 4 * ldb + k0), a, acc[1]);
;                     acc[2] = MFMA16(*(const bf16x8*)(bp + 128 * ldb + k0), a, acc[2]); acc[3] = MFMA16(*(const bf16x8*)(bp + 132 * ldb + k0), a, acc[3]); }
.LBB0_199:
	v_lshl_add_u64 v[30:31], v[26:27], 0, v[24:25]
	s_mov_b32 s0, 0x200000
	v_add_co_u32_e32 v36, vcc, s0, v30
	v_lshl_add_u64 v[16:17], v[28:29], 0, v[24:25]
	s_nop 0
	v_addc_co_u32_e32 v37, vcc, 0, v31, vcc
	global_load_dwordx4 v[44:47], v[16:17], off offset:-256
	global_load_dwordx4 v[48:51], v[16:17], off offset:-192
	global_load_dwordx4 v[52:55], v[16:17], off offset:-128
	global_load_dwordx4 v[56:59], v[16:17], off offset:-64
	global_load_dwordx4 v[60:63], v[16:17], off offset:0
	global_load_dwordx4 v[64:67], v[16:17], off offset:64
	global_load_dwordx4 v[68:71], v[16:17], off offset:128
	s_nop 0
	global_load_dwordx4 v[16:19], v[16:17], off offset:192
	s_mov_b32 s0, 0x202000
	v_add_co_u32_e64 v34, s[0:1], s0, v30
	s_mov_b32 s2, 0x240000
	s_nop 0
	v_addc_co_u32_e64 v35, vcc, 0, v31, s[0:1]
	v_add_co_u32_e64 v32, s[2:3], s2, v30
	s_mov_b32 s4, 0x242000
	s_nop 0
	v_addc_co_u32_e64 v33, vcc, 0, v31, s[2:3]
	v_add_co_u32_e64 v30, s[4:5], s4, v30
	s_addk_i32 s65, 0x100
	s_nop 0
	v_addc_co_u32_e64 v31, vcc, 0, v31, s[4:5]
	v_lshl_add_u64 v[26:27], v[26:27], 0, s[48:49]
	v_lshl_add_u64 v[28:29], v[28:29], 0, s[48:49]
	global_load_dwordx4 v[76:79], v[36:37], off
	global_load_dwordx4 v[80:83], v[34:35], off
	global_load_dwordx4 v[84:87], v[32:33], off
	global_load_dwordx4 v[88:91], v[30:31], off
	global_load_dwordx4 v[92:95], v[36:37], off offset:64
	global_load_dwordx4 v[96:99], v[34:35], off offset:64
	global_load_dwordx4 v[100:103], v[32:33], off offset:64
	global_load_dwordx4 v[104:107], v[30:31], off offset:64
	global_load_dwordx4 v[108:111], v[36:37], off offset:128
	global_load_dwordx4 v[112:115], v[34:35], off offset:128
	global_load_dwordx4 v[116:119], v[32:33], off offset:128
	global_load_dwordx4 v[120:123], v[30:31], off offset:128
	global_load_dwordx4 v[124:127], v[36:37], off offset:192
	global_load_dwordx4 v[128:131], v[34:35], off offset:192
	global_load_dwordx4 v[132:135], v[32:33], off offset:192
	global_load_dwordx4 v[136:139], v[30:31], off offset:192
	global_load_dwordx4 v[140:143], v[36:37], off offset:256
	global_load_dwordx4 v[144:147], v[34:35], off offset:256
	global_load_dwordx4 v[148:151], v[32:33], off offset:256
	global_load_dwordx4 v[152:155], v[30:31], off offset:256
	global_load_dwordx4 v[156:159], v[36:37], off offset:320
	global_load_dwordx4 v[160:163], v[34:35], off offset:320
	global_load_dwordx4 v[164:167], v[32:33], off offset:320
	global_load_dwordx4 v[168:171], v[30:31], off offset:320
	global_load_dwordx4 v[172:175], v[36:37], off offset:384
	global_load_dwordx4 v[176:179], v[34:35], off offset:384
	global_load_dwordx4 v[180:183], v[32:33], off offset:384
	global_load_dwordx4 v[184:187], v[30:31], off offset:384
	global_load_dwordx4 v[188:191], v[36:37], off offset:448
	global_load_dwordx4 v[192:195], v[34:35], off offset:448
	global_load_dwordx4 v[198:201], v[32:33], off offset:448
	global_load_dwordx4 v[202:205], v[30:31], off offset:448
	s_waitcnt vmcnt(28)
	v_mfma_f32_16x16x32_bf16 v[4:7], v[76:79], v[44:47], v[4:7]
	v_mfma_f32_16x16x32_bf16 v[0:3], v[80:83], v[44:47], v[0:3]
	v_mfma_f32_16x16x32_bf16 v[8:11], v[84:87], v[44:47], v[8:11]
	v_mfma_f32_16x16x32_bf16 v[12:15], v[88:91], v[44:47], v[12:15]
	s_waitcnt vmcnt(24)
	v_mfma_f32_16x16x32_bf16 v[4:7], v[92:95], v[48:51], v[4:7]
	v_mfma_f32_16x16x32_bf16 v[0:3], v[96:99], v[48:51], v[0:3]
	v_mfma_f32_16x16x32_bf16 v[8:11], v[100:103], v[48:51], v[8:11]
	v_mfma_f32_16x16x32_bf16 v[12:15], v[104:107], v[48:51], v[12:15]
	s_waitcnt vmcnt(20)
	v_mfma_f32_16x16x32_bf16 v[4:7], v[108:111], v[52:55], v[4:7]
	v_mfma_f32_16x16x32_bf16 v[0:3], v[112:115], v[52:55], v[0:3]
	v_mfma_f32_16x16x32_bf16 v[8:11], v[116:119], v[52:55], v[8:11]
	v_mfma_f32_16x16x32_bf16 v[12:15], v[120:123], v[52:55], v[12:15]
	s_waitcnt vmcnt(16)
	v_mfma_f32_16x16x32_bf16 v[4:7], v[124:127], v[56:59], v[4:7]
	v_mfma_f32_16x16x32_bf16 v[0:3], v[128:131], v[56:59], v[0:3]
	v_mfma_f32_16x16x32_bf16 v[8:11], v[132:135], v[56:59], v[8:11]
	v_mfma_f32_16x16x32_bf16 v[12:15], v[136:139], v[56:59], v[12:15]
	s_waitcnt vmcnt(12)
	v_mfma_f32_16x16x32_bf16 v[4:7], v[140:143], v[60:63], v[4:7]
	v_mfma_f32_16x16x32_bf16 v[0:3], v[144:147], v[60:63], v[0:3]
	v_mfma_f32_16x16x32_bf16 v[8:11], v[148:151], v[60:63], v[8:11]
	v_mfma_f32_16x16x32_bf16 v[12:15], v[152:155], v[60:63], v[12:15]
	s_waitcnt vmcnt(8)
	v_mfma_f32_16x16x32_bf16 v[4:7], v[156:159], v[64:67], v[4:7]
	v_mfma_f32_16x16x32_bf16 v[0:3], v[160:163], v[64:67], v[0:3]
	v_mfma_f32_16x16x32_bf16 v[8:11], v[164:167], v[64:67], v[8:11]
	v_mfma_f32_16x16x32_bf16 v[12:15], v[168:171], v[64:67], v[12:15]
	s_waitcnt vmcnt(4)
	v_mfma_f32_16x16x32_bf16 v[4:7], v[172:175], v[68:71], v[4:7]
	v_mfma_f32_16x16x32_bf16 v[0:3], v[176:179], v[68:71], v[0:3]
	v_mfma_f32_16x16x32_bf16 v[8:11], v[180:183], v[68:71], v[8:11]
	v_mfma_f32_16x16x32_bf16 v[12:15], v[184:187], v[68:71], v[12:15]
	s_waitcnt vmcnt(0)
	v_mfma_f32_16x16x32_bf16 v[4:7], v[188:191], v[16:19], v[4:7]
	v_mfma_f32_16x16x32_bf16 v[0:3], v[192:195], v[16:19], v[0:3]
	v_mfma_f32_16x16x32_bf16 v[8:11], v[198:201], v[16:19], v[8:11]
	v_mfma_f32_16x16x32_bf16 v[12:15], v[202:205], v[16:19], v[12:15]
	s_cmpk_gt_u32 s65, 0x1df
	s_cbranch_scc0 .LBB0_199
	s_mov_b64 s[0:1], 0

; #define MFMA16(a, b, c) __builtin_amdgcn_mfma_f32_16x16x32_bf16((a), (b), (c), 0, 0, 0)
;     ...
;             } else {
; #pragma unroll 8
;                 for (int k0 = 0; k0 < Kh; k0 += 32) { const bf16x8 a = *(const bf16x8*)(ap + k0);
;                     acc[0] = MFMA16(*(const bf16x8*)(bp + k0), a, acc[0]); acc[1] = MFMA16(*(const bf16x8*)(bp + 4 * ldb + k0), a, acc[1]); }
;             }
.LBB0_203:
	v_lshl_add_u64 v[30:31], v[8:9], 0, v[24:25]
	v_add_co_u32_e32 v56, vcc, 0x200000, v30
	v_lshl_add_u64 v[52:53], v[10:11], 0, v[24:25]
	s_nop 0
	v_addc_co_u32_e32 v57, vcc, 0, v31, vcc
	v_add_co_u32_e32 v58, vcc, 0x202000, v30
	s_addk_i32 s0, 0x100
	s_nop 0
	v_addc_co_u32_e32 v59, vcc, 0, v31, vcc
	v_lshl_add_u64 v[8:9], v[8:9], 0, s[48:49]
	v_lshl_add_u64 v[10:11], v[10:11], 0, s[48:49]
	global_load_dwordx4 v[76:79], v[52:53], off offset:-256
	global_load_dwordx4 v[80:83], v[52:53], off offset:-192
	global_load_dwordx4 v[84:87], v[52:53], off offset:-128
	global_load_dwordx4 v[88:91], v[52:53], off offset:-64
	global_load_dwordx4 v[92:95], v[52:53], off offset:0
	global_load_dwordx4 v[96:99], v[52:53], off offset:64
	global_load_dwordx4 v[100:103], v[52:53], off offset:128
	global_load_dwordx4 v[104:107], v[52:53], off offset:192
	global_load_dwordx4 v[108:111], v[56:57], off
	global_load_dwordx4 v[112:115], v[58:59], off
	global_load_dwordx4 v[116:119], v[56:57], off offset:64
	global_load_dwordx4 v[120:123], v[58:59], off offset:64
	global_load_dwordx4 v[124:127], v[56:57], off offset:128
	global_load_dwordx4 v[128:131], v[58:59], off offset:128
	global_load_dwordx4 v[132:135], v[56:57], off offset:192
	global_load_dwordx4 v[136:139], v[58:59], off offset:192
	global_load_dwordx4 v[140:143], v[56:57], off offset:256
	global_load_dwordx4 v[144:147], v[58:59], off offset:256
	global_load_dwordx4 v[148:151], v[56:57], off offset:320
	global_load_dwordx4 v[152:155], v[58:59], off offset:320
	global_load_dwordx4 v[156:159], v[56:57], off offset:384
	global_load_dwordx4 v[160:163], v[58:59], off offset:384
	global_load_dwordx4 v[164:167], v[56:57], off offset:448
	global_load_dwordx4 v[168:171], v[58:59], off offset:448
	s_waitcnt vmcnt(14)
	v_mfma_f32_16x16x32_bf16 v[4:7], v[108:111], v[76:79], v[4:7]
	v_mfma_f32_16x16x32_bf16 v[0:3], v[112:115], v[76:79], v[0:3]
	s_waitcnt vmcnt(12)
	v_mfma_f32_16x16x32_bf16 v[4:7], v[116:119], v[80:83], v[4:7]
	v_mfma_f32_16x16x32_bf16 v[0:3], v[120:123], v[80:83], v[0:3]
	s_waitcnt vmcnt(10)
	v_mfma_f32_16x16x32_bf16 v[4:7], v[124:127], v[84:87], v[4:7]
	v_mfma_f32_16x16x32_bf16 v[0:3], v[128:131], v[84:87], v[0:3]
	s_waitcnt vmcnt(8)
	v_mfma_f32_16x16x32_bf16 v[4:7], v[132:135], v[88:91], v[4:7]
	v_mfma_f32_16x16x32_bf16 v[0:3], v[136:139], v[88:91], v[0:3]
	s_waitcnt vmcnt(6)
	v_mfma_f32_16x16x32_bf16 v[4:7], v[140:143], v[92:95], v[4:7]
	v_mfma_f32_16x16x32_bf16 v[0:3], v[144:147], v[92:95], v[0:3]
	s_waitcnt vmcnt(4)
	v_mfma_f32_16x16x32_bf16 v[4:7], v[148:151], v[96:99], v[4:7]
	v_mfma_f32_16x16x32_bf16 v[0:3], v[152:155], v[96:99], v[0:3]
	s_waitcnt vmcnt(2)
	v_mfma_f32_16x16x32_bf16 v[4:7], v[156:159], v[100:103], v[4:7]
	v_mfma_f32_16x16x32_bf16 v[0:3], v[160:163], v[100:103], v[0:3]
	s_waitcnt vmcnt(0)
	v_mfma_f32_16x16x32_bf16 v[4:7], v[164:167], v[104:107], v[4:7]
	v_mfma_f32_16x16x32_bf16 v[0:3], v[168:171], v[104:107], v[0:3]
	s_cmpk_gt_u32 s0, 0x1df
	s_cbranch_scc0 .LBB0_203
	v_mov_b32_e32 v15, 0
	v_mov_b32_e32 v14, v15
	v_mov_b32_e32 v13, v15
	v_mov_b32_e32 v12, v15
	v_mov_b32_e32 v11, v15
	v_mov_b32_e32 v10, v15
	v_mov_b32_e32 v9, v15
	v_mov_b32_e32 v8, v15
